# grid barrier acquire side: no vmcnt drain behind buffer_inv sc1 before the workgroup barrier; leader publishes the local generation before invalidating its own L1
# speedup vs baseline: 1.0007x; 1.0000x over previous
; __device__ __forceinline__ unsigned xb_ld(unsigned* p)              { return __hip_atomic_load(p, __ATOMIC_RELAXED, __HIP_MEMORY_SCOPE_AGENT); }
; __device__ __forceinline__ unsigned xb_add(unsigned* p, unsigned v) { return __hip_atomic_fetch_add(p, v, __ATOMIC_RELAXED, __HIP_MEMORY_SCOPE_AGENT); }
; #define XB_SPIN(cond, bar) do { unsigned _sp = 0; while (cond) { __builtin_amdgcn_s_sleep(1); \
;     if ((++_sp & 255u) == 0u) { if (xb_ld(&(bar)[XB_TMO])) break; if (_sp > XB_SPIN_CAP) { atomicAdd(&(bar)[XB_TMO], 1u); break; } } } } while (0)
; __device__ __forceinline__ void xcd_barrier(const XcdBarrier& b) {
;     ...
;             __builtin_amdgcn_fence(__ATOMIC_RELEASE, "agent");
;             asm volatile("s_waitcnt vmcnt(0)" ::: "memory");
;             const unsigned og = xb_add(&bar[XB_TOP], 1u);
;             const unsigned tg = og / nx;
;             if (og + 1u == (tg + 1u) * nx) xb_add(&bar[XB_TOPGEN], 1u);
;             else XB_SPIN(xb_ld(&bar[XB_TOPGEN]) == tg, bar);
;             __builtin_amdgcn_fence(__ATOMIC_ACQUIRE, "agent");
;             xb_add(&bar[XB_XGEN(b.x)], 1u);
;             asm volatile("s_waitcnt vmcnt(0)" ::: "memory");
;         } else {
;             XB_SPIN(xb_ld(&bar[XB_XGEN(b.x)]) == gen, bar);
;             __builtin_amdgcn_fence(__ATOMIC_ACQUIRE, "agent");
;             asm volatile("s_waitcnt vmcnt(0)" ::: "memory");
.LBB0_45:
	s_or_b64 exec, exec, s[6:7]
	s_waitcnt vmcnt(0)
	buffer_inv sc1
.LBB0_46:
	s_andn2_saveexec_b64 s[4:5], s[4:5]
	s_cbranch_execz .LBB0_64
	s_mov_b64 s[4:5], exec
	buffer_wbl2 sc1
	s_waitcnt lgkmcnt(0)
	s_waitcnt vmcnt(0)
	v_mbcnt_lo_u32_b32 v1, s4, 0
	v_mbcnt_hi_u32_b32 v1, s5, v1
	v_cmp_eq_u32_e32 vcc, 0, v1
	s_and_saveexec_b64 s[6:7], vcc
	s_cbranch_execz .LBB0_49
	s_bcnt1_i32_b64 s4, s[4:5]
	v_mov_b32_e32 v2, s4
	v_readlane_b32 s4, v252, 53
	v_readlane_b32 s5, v252, 54
	s_nop 4
	global_atomic_add v2, v195, v2, s[4:5] sc0

; __device__ __forceinline__ unsigned xb_add(unsigned* p, unsigned v) { return __hip_atomic_fetch_add(p, v, __ATOMIC_RELAXED, __HIP_MEMORY_SCOPE_AGENT); }
; __device__ __forceinline__ void xcd_barrier(const XcdBarrier& b) {
;     ...
;             __builtin_amdgcn_fence(__ATOMIC_ACQUIRE, "agent");
;             xb_add(&bar[XB_XGEN(b.x)], 1u);
;             asm volatile("s_waitcnt vmcnt(0)" ::: "memory");
.LBB0_63:
	s_or_b64 exec, exec, s[4:5]
	v_mov_b32_e32 v0, 0x2000
	s_waitcnt vmcnt(0)
	global_atomic_add v0, v232, s[2:3] offset:1024
	buffer_inv sc1
